# barrier acquire-at-arrival plus system-coherent loads of the one cross-XCD false-shared record (dilated lse) in dil_combine
# baseline (speedup 1.0000x reference)
; __device__ __forceinline__ unsigned pk2(float lo, float hi) { return f2bf(lo) | (f2bf(hi) << 16); }
; __device__ __forceinline__ void phase_dil_combine(const PT a, int lane, int gw, int ngw) {
;     ...
;     for (int tok = gw; tok < M; tok += ngw) {
;         const int h = lane >> 3;
;         const float l0 = lseb[((size_t)0 * M + tok) * 8 + h], l1 = lseb[((size_t)1 * M + tok) * 8 + h], l2 = lseb[((size_t)2 * M + tok) * 8 + h];
;         const float mx = fmaxf(l0, fmaxf(l1, l2)); float w0 = __expf(l0 - mx), w1 = __expf(l1 - mx), w2 = __expf(l2 - mx); const float iw = 1.0f / (w0 + w1 + w2); w0 *= iw; w1 *= iw; w2 *= iw;
;         const f32x4* p0 = (const f32x4*)(oag + ((size_t)0 * M + tok) * 512 + lane * 8); const f32x4* p1 = (const f32x4*)(oag + ((size_t)1 * M + tok) * 512 + lane * 8); const f32x4* p2 = (const f32x4*)(oag + ((size_t)2 * M + tok) * 512 + lane * 8);
;         const f32x4 x0 = w0 * p0[0] + w1 * p1[0] + w2 * p2[0], x1 = w0 * p0[1] + w1 * p1[1] + w2 * p2[1];
;         u32x4 o; o.x = pk2(x0.x, x0.y); o.y = pk2(x0.z, x0.w); o.z = pk2(x1.x, x1.y); o.w = pk2(x1.z, x1.w);
;         *(u32x4*)(oa + (size_t)tok * KCAT + lane * 8) = o;
;     }
.LBB0_106:
	s_nop 0
	v_lshl_add_u64 v[10:11], s[0:1], 0, v[8:9]
	v_add_co_u32_e32 v12, vcc, 0x2c000000, v10
	v_lshl_add_u64 v[30:31], s[0:1], 0, v[6:7]
	s_nop 0
	v_addc_co_u32_e32 v13, vcc, 0, v11, vcc
	global_load_dword v0, v[12:13], off sc0 sc1
	v_add_co_u32_e32 v12, vcc, 0x2c040000, v10
	s_nop 1
	v_addc_co_u32_e32 v13, vcc, 0, v11, vcc
	v_add_co_u32_e32 v10, vcc, 0x2c080000, v10
	global_load_dword v12, v[12:13], off sc0 sc1
	s_nop 0
	v_addc_co_u32_e32 v11, vcc, 0, v11, vcc
	global_load_dword v10, v[10:11], off sc0 sc1
	s_mov_b64 s[14:15], 0x28000000
	v_lshl_add_u64 v[14:15], v[30:31], 0, s[14:15]
	v_lshl_add_u64 v[18:19], v[30:31], 0, s[14:15]
	s_mov_b64 s[14:15], 0x29000000
	v_lshl_add_u64 v[22:23], v[30:31], 0, s[14:15]
	v_lshl_add_u64 v[26:27], v[30:31], 0, s[14:15]
	s_mov_b64 s[14:15], 0x2a000000
	v_lshl_add_u64 v[38:39], v[30:31], 0, s[14:15]
	v_lshl_add_u64 v[42:43], v[30:31], 0, s[14:15]
	global_load_dwordx4 v[14:17], v[14:15], off
	global_load_dwordx4 v[18:21], v[18:19], off offset:16
	global_load_dwordx4 v[22:25], v[22:23], off
	global_load_dwordx4 v[26:29], v[26:27], off offset:16
	global_load_dwordx4 v[38:41], v[38:39], off
	global_load_dwordx4 v[42:45], v[42:43], off offset:16
	s_add_i32 s4, s4, s6
	v_lshl_add_u64 v[6:7], v[6:7], 0, s[10:11]
	v_lshl_add_u64 v[8:9], v[8:9], 0, s[12:13]
	s_cmpk_lt_i32 s4, 0x2000
	s_waitcnt vmcnt(6)
	v_max3_f32 v11, v0, v12, v10
	v_sub_f32_e32 v0, v0, v11
	v_sub_f32_e32 v12, v12, v11
	v_mul_f32_e32 v0, 0x3fb8aa3b, v0
	v_mul_f32_e32 v12, 0x3fb8aa3b, v12
	v_sub_f32_e32 v10, v10, v11
	v_exp_f32_e32 v0, v0
	v_exp_f32_e32 v12, v12
	v_mul_f32_e32 v10, 0x3fb8aa3b, v10
	v_exp_f32_e32 v10, v10
	s_nop 0
	v_add_f32_e32 v11, v0, v12
	v_add_f32_e32 v11, v10, v11
	v_div_scale_f32 v13, s[14:15], v11, v11, 1.0
	v_rcp_f32_e32 v46, v13
	s_nop 0
	v_fma_f32 v47, -v13, v46, 1.0
	v_fmac_f32_e32 v46, v47, v46
	v_div_scale_f32 v47, vcc, 1.0, v11, 1.0
	v_mul_f32_e32 v48, v47, v46
	v_fma_f32 v49, -v13, v48, v47
	v_fmac_f32_e32 v48, v49, v46
	v_fma_f32 v13, -v13, v48, v47
	s_nop 1
	v_div_fmas_f32 v13, v13, v46, v48
	v_div_fixup_f32 v11, v13, v11, 1.0
	v_mul_f32_e32 v12, v12, v11
	v_mul_f32_e32 v0, v0, v11
	v_mul_f32_e32 v10, v10, v11
	s_waitcnt vmcnt(0)
	v_pk_mul_f32 v[22:23], v[22:23], v[12:13] op_sel_hi:[1,0]
	s_nop 0
	v_pk_fma_f32 v[34:35], v[14:15], v[0:1], v[22:23] op_sel_hi:[1,0,1]
	v_pk_mul_f32 v[24:25], v[24:25], v[12:13] op_sel_hi:[1,0]
	s_nop 0
	v_pk_fma_f32 v[36:37], v[16:17], v[0:1], v[24:25] op_sel_hi:[1,0,1]
	v_pk_mul_f32 v[28:29], v[28:29], v[12:13] op_sel_hi:[1,0]
	v_pk_mul_f32 v[12:13], v[26:27], v[12:13] op_sel_hi:[1,0]
	v_pk_fma_f32 v[14:15], v[38:39], v[10:11], v[34:35] op_sel_hi:[1,0,1]
	v_pk_fma_f32 v[12:13], v[18:19], v[0:1], v[12:13] op_sel_hi:[1,0,1]
	v_pk_fma_f32 v[18:19], v[20:21], v[0:1], v[28:29] op_sel_hi:[1,0,1]
	v_bfe_u32 v0, v14, 16, 1
	v_pk_fma_f32 v[16:17], v[40:41], v[10:11], v[36:37] op_sel_hi:[1,0,1]
	v_pk_fma_f32 v[18:19], v[44:45], v[10:11], v[18:19] op_sel_hi:[1,0,1]
	v_pk_fma_f32 v[12:13], v[42:43], v[10:11], v[12:13] op_sel_hi:[1,0,1]
	v_add3_u32 v0, v14, v0, s72
	v_bfe_u32 v10, v15, 16, 1
	v_lshrrev_b32_e32 v0, 16, v0
	v_add3_u32 v10, v15, v10, s72
	v_and_or_b32 v10, v10, s97, v0
	v_bfe_u32 v0, v16, 16, 1
	v_add3_u32 v0, v16, v0, s72
	v_bfe_u32 v11, v17, 16, 1
	v_lshrrev_b32_e32 v0, 16, v0
	v_add3_u32 v11, v17, v11, s72
	v_and_or_b32 v11, v11, s97, v0
	v_bfe_u32 v0, v12, 16, 1
	v_add3_u32 v0, v12, v0, s72
	v_bfe_u32 v12, v13, 16, 1
	v_lshrrev_b32_e32 v0, 16, v0
	v_add3_u32 v12, v13, v12, s72
	v_and_or_b32 v12, v12, s97, v0
	v_bfe_u32 v0, v18, 16, 1
	v_add3_u32 v0, v18, v0, s72
	v_bfe_u32 v13, v19, 16, 1
	v_lshrrev_b32_e32 v0, 16, v0
	v_add3_u32 v13, v19, v13, s72
	v_and_or_b32 v13, v13, s97, v0
	v_lshl_add_u64 v[14:15], s[0:1], 0, v[4:5]
	v_lshl_add_u64 v[4:5], v[4:5], 0, s[8:9]
	global_store_dwordx4 v[14:15], v[10:13], off
	s_cbranch_scc1 .LBB0_106
